# removed the start-of-kernel cooperative-groups grid.sync (nothing published before it); conversion pool split rebalanced N7=24 N6=324 for the faster converter loop
# baseline (speedup 1.0000x reference)
.LBB0_5:
	s_or_b64 exec, exec, s[2:3]
	s_load_dwordx16 s[36:51], s[0:1], 0x0
	v_mov_b32_e32 v65, v183
	s_waitcnt lgkmcnt(0)
	v_writelane_b32 v254, s36, 14
	s_lshl_b32 s21, s22, 3
	v_and_b32_e32 v64, 63, v65
	v_writelane_b32 v254, s37, 15
	v_writelane_b32 v254, s38, 16
	v_writelane_b32 v254, s39, 17
	v_writelane_b32 v254, s40, 18
	v_writelane_b32 v254, s41, 19
	v_writelane_b32 v254, s42, 20
	v_writelane_b32 v254, s43, 21
	v_writelane_b32 v254, s44, 22
	v_writelane_b32 v254, s45, 23
	v_writelane_b32 v254, s46, 24
	v_writelane_b32 v254, s47, 25
	v_writelane_b32 v254, s48, 26
	v_writelane_b32 v254, s49, 27
	v_writelane_b32 v254, s50, 28
	v_writelane_b32 v254, s51, 29
	s_load_dwordx16 s[36:51], s[0:1], 0x40
	v_readfirstlane_b32 s0, v65
	s_ashr_i32 s26, s0, 6
	s_lshl_b32 s0, s20, 3
	s_mov_b64 s[4:5], s[70:71]
	s_waitcnt lgkmcnt(0)
	v_writelane_b32 v254, s36, 30
	v_mbcnt_lo_u32_b32 v185, -1, 0
	s_nop 0
	v_writelane_b32 v254, s37, 31
	v_writelane_b32 v254, s38, 32
	v_writelane_b32 v254, s39, 33
	v_writelane_b32 v254, s40, 34
	v_writelane_b32 v254, s41, 35
	v_writelane_b32 v254, s42, 36
	v_writelane_b32 v254, s43, 37
	v_writelane_b32 v254, s44, 38
	v_writelane_b32 v254, s45, 39
	v_writelane_b32 v254, s46, 40
	v_writelane_b32 v254, s47, 41
	v_writelane_b32 v254, s48, 42
	v_writelane_b32 v254, s49, 43
	v_writelane_b32 v254, s50, 44
	v_writelane_b32 v254, s51, 45
	v_writelane_b32 v254, s0, 46
	s_add_i32 s0, s26, s0
	s_cmpk_gt_i32 s0, 0x207f
	s_cbranch_scc1 .LBB0_24
	v_mbcnt_hi_u32_b32 v0, -1, v185
	v_and_b32_e32 v1, 64, v0
	v_add_u32_e32 v1, 64, v1
	v_xor_b32_e32 v2, 1, v0
	v_cmp_lt_i32_e32 vcc, v2, v1
	s_add_u32 s27, s4, 0x15300000
	s_addc_u32 s28, s5, 0
	v_cndmask_b32_e32 v2, v0, v2, vcc
	v_lshlrev_b32_e32 v66, 2, v2
	v_xor_b32_e32 v2, 2, v0
	v_cmp_lt_i32_e32 vcc, v2, v1
	s_add_u32 s29, s4, 0x29b48000
	s_addc_u32 s30, s5, 0
	v_cndmask_b32_e32 v2, v0, v2, vcc
	v_lshlrev_b32_e32 v67, 2, v2
	v_xor_b32_e32 v2, 4, v0
	v_cmp_lt_i32_e32 vcc, v2, v1
	s_ashr_i32 s1, s0, 31
	s_lshl_b32 s6, s22, 4
	v_cndmask_b32_e32 v2, v0, v2, vcc
	v_lshlrev_b32_e32 v68, 2, v2
	v_xor_b32_e32 v2, 8, v0
	v_cmp_lt_i32_e32 vcc, v2, v1
	s_lshl_b64 s[8:9], s[0:1], 12
	s_add_u32 s7, s4, s8
	v_cndmask_b32_e32 v2, v0, v2, vcc
	v_lshlrev_b32_e32 v69, 2, v2
	v_xor_b32_e32 v2, 16, v0
	s_addc_u32 s9, s5, s9
	v_cmp_lt_i32_e32 vcc, v2, v1
	s_add_u32 s8, s7, 0x15300000
	s_addc_u32 s9, s9, 0
	v_cndmask_b32_e32 v2, v0, v2, vcc
	s_ashr_i32 s7, s6, 31
	v_lshlrev_b32_e32 v70, 2, v2
	v_xor_b32_e32 v2, 32, v0
	s_lshl_b64 s[10:11], s[6:7], 12
	s_lshl_b64 s[12:13], s[0:1], 2
	v_cmp_lt_i32_e32 vcc, v2, v1
	s_add_u32 s12, s4, s12
	s_addc_u32 s13, s5, s13
	v_cndmask_b32_e32 v0, v0, v2, vcc
	v_lshlrev_b32_e32 v71, 2, v0
	v_or_b32_e32 v0, 0x100, v64
	v_or_b32_e32 v2, 0x140, v64
	v_or_b32_e32 v4, 0x180, v64
	v_or_b32_e32 v6, 0x1c0, v64
	s_add_u32 s12, s12, 0x29b48000
	v_cmp_eq_u32_e64 s[2:3], 0, v64
	s_addc_u32 s13, s13, 0
	s_lshl_b64 s[14:15], s[6:7], 2
	s_mov_b64 s[16:17], 0
	v_lshlrev_b32_e32 v72, 4, v64
	v_lshlrev_b32_e32 v73, 4, v0
	v_lshlrev_b32_e32 v74, 4, v2
	v_lshlrev_b32_e32 v75, 4, v4
	v_lshlrev_b32_e32 v76, 4, v6
	v_lshlrev_b32_e32 v77, 3, v64
	v_mov_b32_e32 v78, 0x358637bd
	s_mov_b32 s31, 0x800000
	s_mov_b32 s33, s0
	s_branch .LBB0_19

.LBB0_119:
	s_or_b64 exec, exec, s[0:1]
	v_mov_b32_e32 v157, v183
	s_waitcnt lgkmcnt(0)
	s_barrier
	s_mov_b64 s[14:15], s[70:71]
	v_readfirstlane_b32 s2, v157
	s_cmpk_gt_i32 s20, 0x71
	s_cbranch_scc0 .LBB0_121
	s_mul_i32 s0, s20, 0x144
	s_add_i32 s3, s0, 0xffff7a68
	s_movk_i32 s0, 0x144
	s_cbranch_execz .LBB0_122
	s_branch .LBB0_123
.LBB0_121:
	s_movk_i32 s0, 0x144
.LBB0_122:
	s_movk_i32 s0, 0x18
	s_mul_i32 s3, s20, 0x18
